# stacked: conv staging and tap-weight loads in flight together, softmax bound reused from the prompt phase (no gain-vector reloads in sample start and combine)
# speedup vs baseline: 1.0041x; 1.0041x over previous
.LBB0_1577:
	v_xor_b32_e32 v177, 0x80000000, v0
	v_readlane_b32 s16, v254, 18
	v_readlane_b32 s24, v254, 26
	v_readlane_b32 s25, v254, 27
	s_waitcnt lgkmcnt(0)
	s_barrier
	v_mbcnt_lo_u32_b32 v168, -1, 0
	v_mbcnt_hi_u32_b32 v168, -1, v168
	v_readlane_b32 s26, v254, 28
	v_ashrrev_i32_e32 v169, 31, v168
	v_readlane_b32 s27, v254, 29
	v_readlane_b32 s28, v254, 30
	v_readlane_b32 s29, v254, 31
	s_mov_b64 s[8:9], s[24:25]
	v_lshlrev_b64 v[174:175], 2, v[168:169]
	s_mov_b64 s[10:11], s[26:27]
	s_mov_b64 s[12:13], s[28:29]
	v_lshl_add_u64 v[170:171], s[10:11], 0, v[174:175]
	v_lshl_add_u64 v[172:173], s[12:13], 0, v[174:175]
	v_readlane_b32 s17, v254, 19
	v_readlane_b32 s18, v254, 20
	v_readlane_b32 s19, v254, 21
	v_readlane_b32 s20, v254, 22
	v_readlane_b32 s21, v254, 23
	v_readlane_b32 s22, v254, 24
	v_readlane_b32 s23, v254, 25
	v_readlane_b32 s30, v254, 32
	v_readlane_b32 s31, v254, 33
	v_cmp_gt_i32_e64 s[2:3], 16, v168
	v_and_b32_e32 v0, 0x7fffffff, v2
	v_and_b32_e32 v1, 0x7fffffff, v3
	s_mov_b64 s[0:1], exec
	v_writelane_b32 v255, s2, 2
	s_nop 1
	v_writelane_b32 v255, s3, 3
	s_and_b64 s[2:3], s[0:1], s[2:3]
	s_mov_b64 exec, s[2:3]
	s_cbranch_execz .LBB0_1579
	v_max_f32_e64 v2, |v2|, |v2|
	v_max_f32_e64 v3, |v3|, |v3|
	v_max_f32_e64 v0, |v0|, |v0|
	v_max_f32_e64 v1, |v1|, |v1|
	v_max_f32_e32 v0, v2, v0
	v_max_f32_e32 v1, v3, v1

.LBB0_1594:
	v_or_b32_e32 v2, s15, v176
	v_ashrrev_i32_e32 v3, 31, v2
	v_lshlrev_b64 v[0:1], 8, v[2:3]
	v_lshl_add_u64 v[4:5], s[86:87], 0, v[0:1]
	v_and_b32_e32 v0, 0xffffffe0, v168
	v_ashrrev_i32_e32 v1, 31, v0
	v_lshl_add_u64 v[4:5], v[4:5], 0, v[0:1]
	s_mov_b64 s[0:1], 0x26b91000
	v_lshl_add_u64 v[6:7], v[4:5], 0, s[0:1]
	s_mov_b32 s0, 0x26b91000
	v_add_co_u32_e32 v8, vcc, s0, v4
	s_mov_b64 s[0:1], 0x26b93000
	s_waitcnt lgkmcnt(0)
	s_barrier
	v_addc_co_u32_e32 v9, vcc, 0, v5, vcc
	global_load_dwordx4 v[36:39], v[6:7], off offset:16
	global_load_dwordx4 v[40:43], v[6:7], off offset:64
	global_load_dwordx4 v[44:47], v[6:7], off offset:80
	global_load_dwordx4 v[48:51], v[6:7], off offset:128
	global_load_dwordx4 v[32:35], v[8:9], off
	global_load_dwordx4 v[60:63], v[6:7], off offset:208
	global_load_dwordx4 v[52:55], v[6:7], off offset:144
	global_load_dwordx4 v[56:59], v[6:7], off offset:192
	v_lshl_add_u64 v[6:7], v[4:5], 0, s[0:1]
	s_mov_b32 s0, 0x26b93000
	v_add_co_u32_e32 v8, vcc, s0, v4
	s_mov_b64 s[0:1], 0x26b93040
	s_nop 0
	v_addc_co_u32_e32 v9, vcc, 0, v5, vcc
	global_load_dwordx4 v[64:67], v[8:9], off
	global_load_dwordx4 v[68:71], v[6:7], off offset:16
	v_lshl_add_u64 v[6:7], v[4:5], 0, s[0:1]
	s_mov_b64 s[0:1], 0x26b93080
	v_lshl_add_u64 v[10:11], v[4:5], 0, s[0:1]
	s_mov_b64 s[0:1], 0x26b930c0
	global_load_dwordx4 v[72:75], v[8:9], off offset:64
	global_load_dwordx4 v[80:83], v[8:9], off offset:128
	v_lshl_add_u64 v[4:5], v[4:5], 0, s[0:1]
	global_load_dwordx4 v[76:79], v[6:7], off offset:16
	global_load_dwordx4 v[88:91], v[8:9], off offset:192
	global_load_dwordx4 v[84:87], v[10:11], off offset:16
	global_load_dwordx4 v[92:95], v[4:5], off offset:16
	s_waitcnt vmcnt(0)
	v_readlane_b32 s0, v255, 4
	v_add_u32_e32 v178, s15, v168
	v_readlane_b32 s1, v255, 5
	s_mov_b32 s19, 0
	s_and_b64 vcc, exec, s[0:1]
	v_cmp_eq_u32_e64 s[4:5], 0, v178
	s_cbranch_vccz .LBB0_1636
	v_max_f32_e32 v1, v97, v97
	v_max_f32_e32 v3, v31, v31
	v_max_f32_e32 v1, v3, v1
	v_max_f32_e32 v3, v96, v96
	v_max_f32_e32 v4, v30, v30
	v_max_f32_e32 v3, v4, v3
	v_mul_f32_e32 v1, 0x411cc471, v1
	v_mul_f32_e32 v1, v1, v3
	v_mul_f32_e32 v1, 0x3fb8aa3b, v1
	v_lshlrev_b32_e32 v4, 3, v168
	s_lshl_b32 s1, s91, 3
	v_and_b32_e32 v1, 15, v168
	v_ashrrev_i32_e32 v3, 4, v168
	v_lshrrev_b32_e32 v5, 3, v178
	v_and_b32_e32 v4, 56, v4
	s_movk_i32 s12, 0x250
	s_bfe_u32 s0, s61, 0x10006
	s_and_b32 s1, s1, 0x1ffffff0
	v_ashrrev_i32_e32 v6, 6, v178
	s_movk_i32 s2, 0x110
	v_lshl_add_u32 v3, s0, 2, v3
	v_or_b32_e32 v9, s1, v1
	v_lshl_or_b32 v10, s0, 4, v1
	v_mad_u64_u32 v[4:5], s[0:1], v5, s12, v[4:5]
	v_mul_lo_u32 v7, v6, s2
	v_and_b32_e32 v8, 63, v168
	s_add_i32 s0, 0, 0x18f00
	v_lshl_add_u32 v7, v8, 2, v7
	v_mul_lo_u32 v6, v6, s12
	v_lshlrev_b32_e32 v8, 3, v8
	v_add_u32_e32 v5, s0, v0
	s_add_i32 s0, 0, 0x13a00
	s_lshl_b32 s1, s15, 2
	v_add3_u32 v201, v6, v8, 0
	v_lshl_add_u32 v6, v9, 2, s0
	v_lshl_add_u32 v202, v2, 2, s0
	s_add_i32 s0, s0, s1
	v_lshlrev_b32_e32 v2, 2, v168
	v_add_u32_e32 v203, s0, v2
	s_add_i32 s0, 0, 0x12800
	v_mul_lo_u32 v12, v9, s12
	v_mov_b32_e32 v14, s0
	v_lshl_add_u32 v9, v9, 1, s0
	s_movk_i32 s0, 0x90
	v_mad_u32_u24 v14, v176, s0, v14
	s_lshl_b32 s18, s91, 5
	v_and_b32_e32 v17, 16, v168
	v_and_b32_e32 v2, 12, v2
	s_add_i32 s0, 0, 0x1d300
	v_or3_b32 v2, v2, v17, s18
	v_mov_b32_e32 v17, s0
	s_add_i32 s0, 0, 0x18c00
	v_and_b32_e32 v18, 0x3ffffff0, v178
	s_add_i32 s13, 0, 0x14200
	s_add_i32 s14, s0, s15
	v_lshlrev_b32_e32 v18, 2, v18
	v_lshlrev_b32_e32 v1, 2, v1
	v_lshl_add_u32 v205, v178, 2, s0
	v_add3_u32 v206, s0, v18, v1
	s_movk_i32 s0, 0x240
	s_add_u32 s15, s86, 0x25f09000
	v_lshlrev_b32_e32 v13, 8, v3
	v_mul_lo_u32 v3, v3, s0
	s_addc_u32 s16, s87, 0
	s_lshl_b64 s[0:1], s[18:19], 2
	v_ashrrev_i32_e32 v200, 5, v168
	s_add_u32 s0, s86, s0
	v_lshlrev_b32_e32 v15, 3, v200
	v_bfe_u32 v16, v168, 2, 2
	s_addc_u32 s1, s87, s1
	v_or_b32_e32 v19, v15, v16
	v_add_u32_e32 v20, 16, v15
	v_add_u32_e32 v22, 32, v15
	v_add_u32_e32 v15, 48, v15
	s_add_u32 s17, s0, 0x26389000
	v_readlane_b32 s36, v254, 2
	v_mov_b32_e32 v11, s13
	v_lshlrev_b32_e32 v21, 1, v20
	v_or_b32_e32 v20, v20, v16
	v_lshlrev_b32_e32 v23, 1, v22
	v_or_b32_e32 v22, v22, v16
	v_lshlrev_b32_e32 v24, 1, v15
	v_or_b32_e32 v15, v15, v16
	s_addc_u32 s18, s1, 0
	v_lshlrev_b32_e32 v180, 4, v178
	v_mov_b32_e32 v181, 0
	v_readlane_b32 s37, v254, 3
	v_readlane_b32 s38, v254, 4
	v_readlane_b32 s40, v254, 6
	v_readlane_b32 s41, v254, 7
	v_readlane_b32 s42, v254, 8
	v_readlane_b32 s43, v254, 9
	v_mul_u32_u24_e32 v8, 0x110, v176
	v_mad_u32_u24 v10, v10, s12, v11
	v_and_b32_e32 v11, -16, v168
	v_add_u32_e32 v12, 0, v12
	v_lshl_add_u32 v2, v2, 1, 0
	v_mad_u32_u24 v17, v176, s2, v17
	v_mad_u32_u24 v1, v176, s12, 0
	v_lshlrev_b32_e32 v18, 4, v200
	v_mul_lo_u32 v19, v19, s12
	v_mul_lo_u32 v20, v20, s12
	v_mul_lo_u32 v22, v22, s12
	v_mul_lo_u32 v15, v15, s12
	s_add_u32 s20, s86, 0x20000
	v_lshl_add_u64 v[182:183], s[40:41], 0, v[180:181]
	v_lshl_add_u64 v[184:185], s[42:43], 0, v[180:181]
	v_cmp_gt_u32_e64 s[6:7], 32, v168
	v_add_u32_e32 v204, 0x9400, v201
	v_cmp_gt_i32_e64 s[8:9], 32, v178
	v_ashrrev_i32_e32 v179, 31, v178
	s_addc_u32 s21, s87, 0
	s_movk_i32 s22, 0x2000
	s_movk_i32 s24, 0x4000
	s_movk_i32 s25, 0x6000
	s_mov_b32 s26, 0x8000
	s_mov_b32 s27, 0xa000
	s_mov_b32 s28, 0xc000
	s_mov_b32 s29, 0xe000
	s_movk_i32 s30, 0x480
	s_mov_b32 s31, 0x38e38e39
	s_movk_i32 s34, 0x120
	s_movk_i32 s35, 0x280
	s_movk_i32 s36, 0x80
	v_add_u32_e32 v207, v5, v8
	v_mov_b32_e32 v208, 0x7f7f7f7f
	v_mov_b32_e32 v209, 0x358637bd
	s_mov_b32 s37, 0xf800000
	v_mov_b32_e32 v210, 0x260
	s_movk_i32 s38, 0x7fff
	v_add_u32_e32 v211, v17, v0
	v_add_u32_e32 v212, 0, v7
	v_add_u32_e32 v213, 0, v4
	v_add_u32_e32 v214, v1, v0
	v_add_u32_e32 v215, v10, v11
	v_add_u32_e32 v216, v12, v11
	v_add_u32_e32 v217, v6, v13
	v_add_u32_e32 v218, v9, v3
	v_add_u32_e32 v219, v14, v18
	v_add_u32_e32 v220, v2, v19
	v_add_u32_e32 v221, v14, v21
	v_add_u32_e32 v222, v2, v20
	v_add_u32_e32 v223, v14, v23
	v_add_u32_e32 v224, v2, v22
	v_add_u32_e32 v225, v14, v24
	v_add_u32_e32 v226, v2, v15
	v_readlane_b32 s39, v254, 5
	v_readlane_b32 s44, v254, 10
	v_readlane_b32 s45, v254, 11
	v_readlane_b32 s46, v254, 12
	v_readlane_b32 s47, v254, 13
	v_readlane_b32 s48, v254, 14
	v_readlane_b32 s49, v254, 15
	v_readlane_b32 s50, v254, 16
	v_readlane_b32 s51, v254, 17
	s_branch .LBB0_1597

.LBB0_1654:
	s_or_b64 exec, exec, s[0:1]
	s_andn2_b64 vcc, exec, s[10:11]
	s_barrier
	s_cbranch_vccnz .LBB0_1638
	v_and_b32_e32 v23, 0x7fffffff, v0
	v_and_b32_e32 v22, 0x7fffffff, v1
	s_mov_b64 s[0:1], exec
	v_readlane_b32 s2, v255, 2
	v_readlane_b32 s3, v255, 3
	s_and_b64 s[2:3], s[0:1], s[2:3]
	s_mov_b64 exec, s[2:3]
	s_cbranch_execz .LBB0_1657
	v_max_f32_e64 v0, |v0|, |v0|
	v_max_f32_e64 v1, |v1|, |v1|
	v_max_f32_e64 v2, |v2|, |v2|
	v_max_f32_e64 v3, |v3|, |v3|
	v_max_f32_e32 v23, v0, v2
	v_max_f32_e32 v22, v1, v3

.LBB0_1685:
	s_or_b64 exec, exec, s[0:1]
	v_max_f32_e32 v77, v77, v77
	v_max_f32_e32 v75, v75, v75
	v_max_f32_e32 v75, v75, v77
	v_max_f32_e32 v76, v76, v76
	v_max_f32_e32 v74, v74, v74
	v_max_f32_e32 v74, v74, v76
	v_mul_f32_e32 v75, 0x411cc471, v75
	v_mul_f32_e32 v74, v75, v74
	v_add_f32_e32 v75, v90, v91
	v_fmamk_f32 v75, v75, 0x3c2aaaab, v41
	v_mul_f32_e32 v76, 0x4f800000, v75
	v_cmp_gt_f32_e32 vcc, s38, v75
	v_add_f32_e32 v67, 0, v67
	v_add_f32_e32 v66, v67, v66
	v_cndmask_b32_e32 v75, v75, v76, vcc
	v_sqrt_f32_e32 v76, v75
	v_add_f32_e32 v65, 0, v65
	v_add_f32_e32 v64, v65, v64
	v_add_f32_e32 v65, v84, v85
	v_add_u32_e32 v77, -1, v76
	v_fma_f32 v90, -v77, v76, v75
	v_cmp_ge_f32_e64 s[0:1], 0, v90
	v_add_u32_e32 v90, 1, v76
	v_fmamk_f32 v65, v65, 0x3c2aaaab, v41
	v_cndmask_b32_e64 v77, v76, v77, s[0:1]
	v_fma_f32 v76, -v90, v76, v75
	v_cmp_lt_f32_e64 s[0:1], 0, v76
	v_add_f32_e32 v53, 0, v53
	v_add_f32_e32 v55, 0, v55
	v_cndmask_b32_e64 v76, v77, v90, s[0:1]
	v_mul_f32_e32 v77, 0x37800000, v76
	v_cndmask_b32_e32 v76, v76, v77, vcc
	v_cmp_class_f32_e32 vcc, v75, v43
	v_add_f32_e32 v90, 0, v45
	v_add_f32_e32 v60, 0, v60
	v_cndmask_b32_e32 v75, v76, v75, vcc
	v_div_scale_f32 v76, s[0:1], v75, v75, 1.0
	v_rcp_f32_e32 v77, v76
	v_add_f32_e32 v59, v60, v59
	v_mul_f32_e32 v74, 0x3fb8aa3b, v74
	v_mov_b32_e32 v74, v177
	v_fma_f32 v45, -v76, v77, 1.0
	v_fmac_f32_e32 v77, v45, v77
	v_div_scale_f32 v45, vcc, 1.0, v75, 1.0
	v_mul_f32_e32 v67, v45, v77
	v_fma_f32 v91, -v76, v67, v45
	v_fmac_f32_e32 v67, v91, v77
	v_fma_f32 v45, -v76, v67, v45
	v_div_fmas_f32 v45, v45, v77, v67
	v_mul_f32_e32 v76, 0x4f800000, v65
	v_cmp_gt_f32_e32 vcc, s38, v65
	v_div_fixup_f32 v67, v45, v75, 1.0
	v_add_f32_e32 v45, v88, v89
	v_cndmask_b32_e32 v65, v65, v76, vcc
	v_sqrt_f32_e32 v76, v65
	v_add_f32_e32 v88, v53, v61
	v_add_f32_e32 v38, 0, v38
	v_add_f32_e32 v38, v38, v48
	v_add_u32_e32 v84, -1, v76
	v_fma_f32 v85, -v84, v76, v65
	v_cmp_ge_f32_e64 s[0:1], 0, v85
	v_add_u32_e32 v85, 1, v76
	v_add_f32_e32 v26, v26, v27
	v_cndmask_b32_e64 v84, v76, v84, s[0:1]
	v_fma_f32 v76, -v85, v76, v65
	v_cmp_lt_f32_e64 s[0:1], 0, v76
	v_add_f32_e32 v40, 0, v40
	v_add_f32_e32 v35, 0, v35
	v_cndmask_b32_e64 v76, v84, v85, s[0:1]
	v_mul_f32_e32 v84, 0x37800000, v76
	v_cndmask_b32_e32 v76, v76, v84, vcc
	v_cmp_class_f32_e32 vcc, v65, v43
	v_add_f32_e32 v85, 0, v51
	v_add_f32_e32 v40, v40, v42
	v_cndmask_b32_e32 v65, v76, v65, vcc
	v_div_scale_f32 v76, s[0:1], v65, v65, 1.0
	v_rcp_f32_e32 v84, v76
	v_add_f32_e32 v35, v35, v44
	s_waitcnt vmcnt(4)
	v_lshlrev_b32_e32 v77, 16, v100
	v_mul_f32_e32 v24, v25, v24
	v_fma_f32 v51, -v76, v84, 1.0
	v_fmac_f32_e32 v84, v51, v84
	v_div_scale_f32 v51, vcc, 1.0, v65, 1.0
	v_mul_f32_e32 v53, v51, v84
	v_fma_f32 v61, -v76, v53, v51
	v_fmac_f32_e32 v53, v61, v84
	v_fma_f32 v51, -v76, v53, v51
	v_add_f32_e32 v76, v55, v57
	v_add_f32_e32 v57, v71, v72
	v_fmamk_f32 v57, v57, 0x3c2aaaab, v41
	v_div_fmas_f32 v51, v51, v84, v53
	v_mul_f32_e32 v60, 0x4f800000, v57
	v_cmp_gt_f32_e32 vcc, s38, v57
	v_div_fixup_f32 v61, v51, v65, 1.0
	v_add_f32_e32 v51, v82, v83
	v_cndmask_b32_e32 v57, v57, v60, vcc
	v_sqrt_f32_e32 v60, v57
	v_add_f32_e32 v53, v86, v87
	v_add_f32_e32 v55, v92, v93
	v_fma_f32 v51, v61, v51, -v74
	v_fma_f32 v53, v61, v53, -v74
	v_fma_f32 v55, v61, v55, -v74
	v_add_u32_e32 v61, -1, v60
	v_fma_f32 v65, -v61, v60, v57
	v_cmp_ge_f32_e64 s[0:1], 0, v65
	v_add_u32_e32 v65, 1, v60
	v_mul_f32_e32 v24, v52, v24
	v_cndmask_b32_e64 v61, v60, v61, s[0:1]
	v_fma_f32 v60, -v65, v60, v57
	v_cmp_lt_f32_e64 s[0:1], 0, v60
	v_add_f32_e32 v32, 0, v32
	v_add_f32_e32 v31, v32, v31
	v_cndmask_b32_e64 v60, v61, v65, s[0:1]
	v_mul_f32_e32 v61, 0x37800000, v60
	v_cndmask_b32_e32 v60, v60, v61, vcc
	v_cmp_class_f32_e32 vcc, v57, v43
	v_add_f32_e32 v36, 0, v36
	v_add_f32_e32 v36, v36, v46
	v_cndmask_b32_e32 v57, v60, v57, vcc
	v_div_scale_f32 v60, s[0:1], v57, v57, 1.0
	v_rcp_f32_e32 v61, v60
	v_add_f32_e32 v68, 0, v68
	v_fma_f32 v45, v67, v45, -v74
	v_add_f32_e32 v68, v68, v47
	v_fma_f32 v48, -v60, v61, 1.0
	v_fmac_f32_e32 v61, v48, v61
	v_div_scale_f32 v48, vcc, 1.0, v57, 1.0
	v_mul_f32_e32 v65, v48, v61
	v_fma_f32 v71, -v60, v65, v48
	v_fmac_f32_e32 v65, v71, v61
	v_fma_f32 v48, -v60, v65, v48
	v_div_fmas_f32 v48, v48, v61, v65
	v_div_fixup_f32 v48, v48, v57, 1.0
	v_fma_f32 v26, v48, v26, -v74
	v_exp_f32_e32 v61, v26
	v_add_f32_e32 v26, v62, v63
	v_fmamk_f32 v26, v26, 0x3c2aaaab, v41
	v_mul_f32_e32 v27, 0x4f800000, v26
	v_cmp_gt_f32_e32 vcc, s38, v26
	v_add_f32_e32 v47, v98, v99
	v_exp_f32_e32 v45, v45
	v_cndmask_b32_e32 v26, v26, v27, vcc
	v_sqrt_f32_e32 v27, v26
	v_add_f32_e32 v75, v90, v49
	v_fma_f32 v47, v67, v47, -v74
	s_waitcnt lgkmcnt(0)
	v_add_f32_e32 v49, v101, v102
	v_add_u32_e32 v42, -1, v27
	v_fma_f32 v44, -v42, v27, v26
	v_cmp_ge_f32_e64 s[0:1], 0, v44
	v_add_u32_e32 v44, 1, v27
	v_add_f32_e32 v57, v69, v70
	v_cndmask_b32_e64 v42, v27, v42, s[0:1]
	v_fma_f32 v27, -v44, v27, v26
	v_cmp_lt_f32_e64 s[0:1], 0, v27
	v_exp_f32_e32 v47, v47
	v_fma_f32 v49, v67, v49, -v74
	v_cndmask_b32_e64 v27, v42, v44, s[0:1]
	v_mul_f32_e32 v42, 0x37800000, v27
	v_cndmask_b32_e32 v27, v27, v42, vcc
	v_mul_f32_e32 v42, v73, v77
	v_fmac_f32_e32 v24, v50, v42
	ds_bpermute_b32 v25, v194, v24
	v_cmp_class_f32_e32 vcc, v26, v43
	v_exp_f32_e32 v51, v51
	v_fma_f32 v57, v48, v57, -v74
	v_cndmask_b32_e32 v26, v27, v26, vcc
	s_waitcnt lgkmcnt(0)
	v_add_f32_e32 v24, v24, v25
	ds_bpermute_b32 v25, v195, v24
	v_div_scale_f32 v27, s[0:1], v26, v26, 1.0
	v_rcp_f32_e32 v42, v27
	v_exp_f32_e32 v49, v49
	s_waitcnt lgkmcnt(0)
	v_add_f32_e32 v24, v24, v25
	ds_bpermute_b32 v25, v196, v24
	v_fma_f32 v32, -v27, v42, 1.0
	v_fmac_f32_e32 v42, v32, v42
	v_div_scale_f32 v32, vcc, 1.0, v26, 1.0
	s_waitcnt lgkmcnt(0)
	v_add_f32_e32 v24, v24, v25
	ds_bpermute_b32 v25, v197, v24
	v_mul_f32_e32 v44, v32, v42
	v_fma_f32 v46, -v27, v44, v32
	v_fmac_f32_e32 v44, v46, v42
	v_fma_f32 v27, -v27, v44, v32
	s_waitcnt lgkmcnt(0)
	v_add_f32_e32 v24, v24, v25
	ds_bpermute_b32 v25, v198, v24
	v_div_fmas_f32 v27, v27, v42, v44
	v_div_fixup_f32 v26, v27, v26, 1.0
	v_add_f32_e32 v27, v54, v56
	v_fma_f32 v26, v26, v27, -v74
	s_waitcnt lgkmcnt(0)
	v_add_f32_e32 v24, v24, v25
	ds_bpermute_b32 v25, v199, v24
	v_exp_f32_e32 v53, v53
	v_exp_f32_e32 v57, v57
	v_exp_f32_e32 v63, v26
	v_lshlrev_b32_e32 v78, 16, v78
	s_waitcnt lgkmcnt(0)
	v_add_f32_e32 v24, v24, v25
	v_fma_f32 v24, v67, v24, -v74
	v_lshlrev_b32_e32 v79, 16, v79
	v_lshlrev_b32_e32 v80, 16, v80
	v_lshlrev_b32_e32 v81, 16, v81
	v_exp_f32_e32 v55, v55
	v_exp_f32_e32 v65, v24
	v_lshlrev_b32_e32 v94, 16, v94
	v_lshlrev_b32_e32 v95, 16, v95
	v_lshlrev_b32_e32 v96, 16, v96
	v_lshlrev_b32_e32 v97, 16, v97
	v_fmac_f32_e32 v66, v45, v78
	v_fmac_f32_e32 v68, v45, v79
	v_fmac_f32_e32 v75, v45, v80
	v_fmac_f32_e32 v64, v45, v81
	v_add_f32_e32 v58, v85, v58
	v_add_f32_e32 v33, 0, v33
	v_lshlrev_b32_e32 v103, 16, v103
	v_lshlrev_b32_e32 v104, 16, v104
	v_lshlrev_b32_e32 v105, 16, v105
	v_lshlrev_b32_e32 v106, 16, v106
	v_fmac_f32_e32 v66, v47, v94
	v_fmac_f32_e32 v68, v47, v95
	v_fmac_f32_e32 v75, v47, v96
	v_fmac_f32_e32 v64, v47, v97
	v_fmac_f32_e32 v88, v51, v78
	v_fmac_f32_e32 v76, v51, v79
	v_fmac_f32_e32 v58, v51, v80
	v_fmac_f32_e32 v59, v51, v81
	v_add_f32_e32 v34, 0, v34
	v_add_f32_e32 v12, 0, v12
	v_add_f32_e32 v26, v33, v28
	s_waitcnt vmcnt(3)
	v_lshlrev_b32_e32 v20, 16, v22
	s_waitcnt vmcnt(2)
	v_lshlrev_b32_e32 v21, 16, v23
	s_waitcnt vmcnt(1)
	v_lshlrev_b32_e32 v22, 16, v107
	s_waitcnt vmcnt(0)
	v_lshlrev_b32_e32 v23, 16, v108
	v_fmac_f32_e32 v66, v49, v103
	v_fmac_f32_e32 v68, v49, v104
	v_fmac_f32_e32 v75, v49, v105
	v_fmac_f32_e32 v64, v49, v106
	v_fmac_f32_e32 v88, v53, v94
	v_fmac_f32_e32 v76, v53, v95
	v_fmac_f32_e32 v58, v53, v96
	v_fmac_f32_e32 v59, v53, v97
	v_fmac_f32_e32 v38, v57, v78
	v_fmac_f32_e32 v40, v57, v79
	v_fmac_f32_e32 v35, v57, v80
	v_fmac_f32_e32 v36, v57, v81
	v_add_f32_e32 v27, v34, v29
	v_add_f32_e32 v12, v12, v30
	v_fmac_f32_e32 v31, v63, v78
	v_fmac_f32_e32 v26, v63, v79
	v_fmac_f32_e32 v88, v55, v103
	v_fmac_f32_e32 v76, v55, v104
	v_fmac_f32_e32 v58, v55, v105
	v_fmac_f32_e32 v59, v55, v106
	v_fmac_f32_e32 v38, v61, v94
	v_fmac_f32_e32 v40, v61, v95
	v_fmac_f32_e32 v35, v61, v96
	v_fmac_f32_e32 v36, v61, v97
	v_fmac_f32_e32 v27, v63, v80
	v_fmac_f32_e32 v12, v63, v81
	v_fmac_f32_e32 v64, v65, v23
	v_fmac_f32_e32 v75, v65, v22
	v_fmac_f32_e32 v68, v65, v21
	v_fmac_f32_e32 v66, v65, v20
	ds_write2st64_b32 v37, v31, v26 offset1:1
	ds_write2st64_b32 v37, v27, v12 offset0:2 offset1:3
	ds_write2st64_b32 v37, v38, v40 offset0:4 offset1:5
	ds_write2st64_b32 v37, v35, v36 offset0:6 offset1:7
	ds_write2st64_b32 v37, v88, v76 offset0:8 offset1:9
	ds_write2st64_b32 v37, v58, v59 offset0:10 offset1:11
	ds_write2st64_b32 v37, v66, v68 offset0:12 offset1:13
	ds_write2st64_b32 v37, v75, v64 offset0:14 offset1:15
	s_waitcnt lgkmcnt(0)
	s_lshl_b32 s0, s19, 6
	s_mov_b32 s1, s9
	v_mov_b32_e32 v24, 0
	s_mov_b32 s2, 0
	v_lshl_add_u64 v[20:21], s[0:1], 2, v[16:17]
	v_mov_b32_e32 v25, v24
	v_mov_b32_e32 v22, v24
	v_mov_b32_e32 v23, v24
